# gemm1 gate-tile sigmoid epilogue: multiply and +1 packed two elements per instruction (same f32 ops)
# baseline (speedup 1.0000x reference)
; __device__ __forceinline__ unsigned cvt_pk_bf16(float lo, float hi) { unsigned r; asm volatile("v_cvt_pk_bf16_f32 %0, %1, %2" : "=v"(r) : "v"(lo), "v"(hi)); return r; }
;     __device__ __forceinline__ void operator()(const f32x4 (&acc)[2][2][4][2], const Unit& u, int wr, int wc, int fr, int fq) const {
;     ...
;         for (int bj = 0; bj < 2; ++bj)
; #pragma unroll
;             for (int n = 0; n < 2; ++n) bv[bj][n] = sig ? *(const f32x4*)(bias1 + col0 + bj * HALF + 4 * n) : (f32x4){0.f, 0.f, 0.f, 0.f};
; #pragma unroll
;         for (int ai = 0; ai < 2; ++ai)
; #pragma unroll
;             for (int m = 0; m < 4; ++m) { bf16_t* rowp = base + (size_t)(row0 + ai * HALF + m * 16) * ld + col0;
; #pragma unroll
;                 for (int bj = 0; bj < 2; ++bj) { f32x4 v0 = acc[ai][bj][m][0] + bv[bj][0], v1 = acc[ai][bj][m][1] + bv[bj][1];
;                     if (sig) {
; #pragma unroll
;                         for (int j = 0; j < 4; ++j) { v0[j] = __builtin_amdgcn_rcpf(1.0f + __expf(-v0[j])); v1[j] = __builtin_amdgcn_rcpf(1.0f + __expf(-v1[j])); } }
;                     u32x4 w; w.x = cvt_pk_bf16(v0[0], v0[1]); w.y = cvt_pk_bf16(v0[2], v0[3]); w.z = cvt_pk_bf16(v1[0], v1[1]); w.w = cvt_pk_bf16(v1[2], v1[3]);
;                     *(u32x4*)(rowp + bj * HALF) = w; } }
.LBB0_565:
	s_waitcnt vmcnt(0)
	v_pk_add_f32 v[144:145], v[144:145], v[88:89]
	v_pk_add_f32 v[142:143], v[142:143], v[86:87]
	v_pk_add_f32 v[158:159], v[140:141], v[84:85]
	s_and_b64 vcc, exec, s[38:39]
	v_pk_add_f32 v[160:161], v[138:139], v[82:83]
	s_cbranch_vccnz .LBB0_567
	s_mov_b32 s100, 0xbfb8aa3b
	v_pk_mul_f32 v[142:143], v[142:143], s[100:101] op_sel_hi:[1,0]
	v_pk_mul_f32 v[144:145], v[144:145], s[100:101] op_sel_hi:[1,0]
	v_pk_mul_f32 v[158:159], v[158:159], s[100:101] op_sel_hi:[1,0]
	v_pk_mul_f32 v[160:161], v[160:161], s[100:101] op_sel_hi:[1,0]
	v_exp_f32_e32 v142, v142
	v_exp_f32_e32 v143, v143
	v_exp_f32_e32 v144, v144
	v_exp_f32_e32 v145, v145
	v_exp_f32_e32 v158, v158
	v_exp_f32_e32 v159, v159
	v_exp_f32_e32 v160, v160
	v_exp_f32_e32 v161, v161
	v_pk_add_f32 v[142:143], v[142:143], 1.0 op_sel_hi:[1,0]
	v_pk_add_f32 v[144:145], v[144:145], 1.0 op_sel_hi:[1,0]
	v_pk_add_f32 v[158:159], v[158:159], 1.0 op_sel_hi:[1,0]
	v_pk_add_f32 v[160:161], v[160:161], 1.0 op_sel_hi:[1,0]
	v_rcp_f32_e32 v142, v142
	v_rcp_f32_e32 v143, v143
	v_rcp_f32_e32 v144, v144
	v_rcp_f32_e32 v145, v145
	v_rcp_f32_e32 v158, v158
	v_rcp_f32_e32 v159, v159
	v_rcp_f32_e32 v160, v160
	v_rcp_f32_e32 v161, v161
.LBB0_567:
	s_and_b64 s[16:17], s[50:51], exec
	s_mov_b32 s13, 0x16c58000
	s_cselect_b32 s13, s13, 0x7c58000
	s_add_u32 s16, s74, s13
	s_addc_u32 s17, s75, 0
	s_and_b64 s[18:19], s[50:51], exec
	s_movk_i32 s13, 0xc00
	s_cselect_b32 s13, s13, 0x1e00
	v_lshl_add_u32 v166, s14, 8, v162
	v_lshl_add_u64 v[138:139], v[156:157], 1, s[16:17]
	v_mad_i64_i32 v[140:141], s[14:15], s13, v166, 0
	v_lshl_add_u64 v[140:141], v[140:141], 1, v[138:139]
	v_pk_add_f32 v[136:137], v[136:137], v[76:77]
	v_pk_add_f32 v[134:135], v[134:135], v[74:75]
	v_pk_add_f32 v[132:133], v[132:133], v[68:69]
	s_and_b64 vcc, exec, s[38:39]
	v_pk_add_f32 v[130:131], v[130:131], v[66:67]
	v_cvt_pk_bf16_f32 v142, v142, v143
	v_cvt_pk_bf16_f32 v143, v144, v145
	v_cvt_pk_bf16_f32 v144, v160, v161
	v_cvt_pk_bf16_f32 v145, v158, v159
	global_store_dwordx4 v[140:141], v[142:145], off sc1
	s_cbranch_vccnz .LBB0_569
	s_mov_b32 s100, 0xbfb8aa3b
	v_pk_mul_f32 v[130:131], v[130:131], s[100:101] op_sel_hi:[1,0]
	v_pk_mul_f32 v[132:133], v[132:133], s[100:101] op_sel_hi:[1,0]
	v_pk_mul_f32 v[134:135], v[134:135], s[100:101] op_sel_hi:[1,0]
	v_pk_mul_f32 v[136:137], v[136:137], s[100:101] op_sel_hi:[1,0]
	v_exp_f32_e32 v130, v130
	v_exp_f32_e32 v131, v131
	v_exp_f32_e32 v132, v132
	v_exp_f32_e32 v133, v133
	v_exp_f32_e32 v134, v134
	v_exp_f32_e32 v135, v135
	v_exp_f32_e32 v136, v136
	v_exp_f32_e32 v137, v137
	v_pk_add_f32 v[130:131], v[130:131], 1.0 op_sel_hi:[1,0]
	v_pk_add_f32 v[132:133], v[132:133], 1.0 op_sel_hi:[1,0]
	v_pk_add_f32 v[134:135], v[134:135], 1.0 op_sel_hi:[1,0]
	v_pk_add_f32 v[136:137], v[136:137], 1.0 op_sel_hi:[1,0]
	v_rcp_f32_e32 v130, v130
	v_rcp_f32_e32 v131, v131
	v_rcp_f32_e32 v132, v132
	v_rcp_f32_e32 v133, v133
	v_rcp_f32_e32 v134, v134
	v_rcp_f32_e32 v135, v135
	v_rcp_f32_e32 v136, v136
	v_rcp_f32_e32 v137, v137
.LBB0_569:
	v_readlane_b32 s16, v255, 27
	v_cvt_pk_bf16_f32 v134, v134, v135
	v_cvt_pk_bf16_f32 v135, v136, v137
	v_cvt_pk_bf16_f32 v136, v130, v131
	v_pk_add_f32 v[128:129], v[128:129], v[88:89]
	v_pk_add_f32 v[126:127], v[126:127], v[86:87]
	v_pk_add_f32 v[124:125], v[124:125], v[84:85]
	s_and_b64 vcc, exec, s[38:39]
	v_pk_add_f32 v[130:131], v[122:123], v[82:83]
	v_readlane_b32 s17, v255, 28
	v_cvt_pk_bf16_f32 v137, v132, v133
	global_store_dwordx4 v[140:141], v[134:137], off offset:256 sc1
	s_cbranch_vccnz .LBB0_571
	s_mov_b32 s100, 0xbfb8aa3b
	v_pk_mul_f32 v[124:125], v[124:125], s[100:101] op_sel_hi:[1,0]
	v_pk_mul_f32 v[126:127], v[126:127], s[100:101] op_sel_hi:[1,0]
	v_pk_mul_f32 v[128:129], v[128:129], s[100:101] op_sel_hi:[1,0]
	v_pk_mul_f32 v[130:131], v[130:131], s[100:101] op_sel_hi:[1,0]
	v_exp_f32_e32 v124, v124
	v_exp_f32_e32 v125, v125
	v_exp_f32_e32 v126, v126
	v_exp_f32_e32 v127, v127
	v_exp_f32_e32 v128, v128
	v_exp_f32_e32 v129, v129
	v_exp_f32_e32 v130, v130
	v_exp_f32_e32 v131, v131
	v_pk_add_f32 v[124:125], v[124:125], 1.0 op_sel_hi:[1,0]
	v_pk_add_f32 v[126:127], v[126:127], 1.0 op_sel_hi:[1,0]
	v_pk_add_f32 v[128:129], v[128:129], 1.0 op_sel_hi:[1,0]
	v_pk_add_f32 v[130:131], v[130:131], 1.0 op_sel_hi:[1,0]
	v_rcp_f32_e32 v124, v124
	v_rcp_f32_e32 v125, v125
	v_rcp_f32_e32 v126, v126
	v_rcp_f32_e32 v127, v127
	v_rcp_f32_e32 v128, v128
	v_rcp_f32_e32 v129, v129
	v_rcp_f32_e32 v130, v130
	v_rcp_f32_e32 v131, v131
.LBB0_571:
	v_or_b32_e32 v122, 16, v166
	v_mad_i64_i32 v[122:123], s[14:15], s13, v122, 0
	v_lshl_add_u64 v[122:123], v[122:123], 1, v[138:139]
	v_pk_add_f32 v[120:121], v[120:121], v[76:77]
	v_pk_add_f32 v[118:119], v[118:119], v[74:75]
	v_pk_add_f32 v[116:117], v[116:117], v[68:69]
	s_and_b64 vcc, exec, s[38:39]
	v_pk_add_f32 v[114:115], v[114:115], v[66:67]
	v_cvt_pk_bf16_f32 v126, v126, v127
	v_cvt_pk_bf16_f32 v127, v128, v129
	v_cvt_pk_bf16_f32 v128, v130, v131
	v_cvt_pk_bf16_f32 v129, v124, v125
	global_store_dwordx4 v[122:123], v[126:129], off sc1
	s_cbranch_vccnz .LBB0_573
	s_mov_b32 s100, 0xbfb8aa3b
	v_pk_mul_f32 v[114:115], v[114:115], s[100:101] op_sel_hi:[1,0]
	v_pk_mul_f32 v[116:117], v[116:117], s[100:101] op_sel_hi:[1,0]
	v_pk_mul_f32 v[118:119], v[118:119], s[100:101] op_sel_hi:[1,0]
	v_pk_mul_f32 v[120:121], v[120:121], s[100:101] op_sel_hi:[1,0]
	v_exp_f32_e32 v114, v114
	v_exp_f32_e32 v115, v115
	v_exp_f32_e32 v116, v116
	v_exp_f32_e32 v117, v117
	v_exp_f32_e32 v118, v118
	v_exp_f32_e32 v119, v119
	v_exp_f32_e32 v120, v120
	v_exp_f32_e32 v121, v121
	v_pk_add_f32 v[114:115], v[114:115], 1.0 op_sel_hi:[1,0]
	v_pk_add_f32 v[116:117], v[116:117], 1.0 op_sel_hi:[1,0]
	v_pk_add_f32 v[118:119], v[118:119], 1.0 op_sel_hi:[1,0]
	v_pk_add_f32 v[120:121], v[120:121], 1.0 op_sel_hi:[1,0]
	v_rcp_f32_e32 v114, v114
	v_rcp_f32_e32 v115, v115
	v_rcp_f32_e32 v116, v116
	v_rcp_f32_e32 v117, v117
	v_rcp_f32_e32 v118, v118
	v_rcp_f32_e32 v119, v119
	v_rcp_f32_e32 v120, v120
	v_rcp_f32_e32 v121, v121
; __device__ __forceinline__ unsigned cvt_pk_bf16(float lo, float hi) { unsigned r; asm volatile("v_cvt_pk_bf16_f32 %0, %1, %2" : "=v"(r) : "v"(lo), "v"(hi)); return r; }
;     __device__ __forceinline__ void operator()(const f32x4 (&acc)[2][2][4][2], const Unit& u, int wr, int wc, int fr, int fq) const {
;     ...
;         for (int ai = 0; ai < 2; ++ai)
; #pragma unroll
;             for (int m = 0; m < 4; ++m) { bf16_t* rowp = base + (size_t)(row0 + ai * HALF + m * 16) * ld + col0;
; #pragma unroll
;                 for (int bj = 0; bj < 2; ++bj) { f32x4 v0 = acc[ai][bj][m][0] + bv[bj][0], v1 = acc[ai][bj][m][1] + bv[bj][1];
;                     if (sig) {
; #pragma unroll
;                         for (int j = 0; j < 4; ++j) { v0[j] = __builtin_amdgcn_rcpf(1.0f + __expf(-v0[j])); v1[j] = __builtin_amdgcn_rcpf(1.0f + __expf(-v1[j])); } }
;                     u32x4 w; w.x = cvt_pk_bf16(v0[0], v0[1]); w.y = cvt_pk_bf16(v0[2], v0[3]); w.z = cvt_pk_bf16(v1[0], v1[1]); w.w = cvt_pk_bf16(v1[2], v1[3]);
;                     *(u32x4*)(rowp + bj * HALF) = w; } }
.LBB0_573:
	v_cvt_pk_bf16_f32 v118, v118, v119
	v_cvt_pk_bf16_f32 v119, v120, v121
	v_cvt_pk_bf16_f32 v120, v114, v115
	v_pk_add_f32 v[112:113], v[112:113], v[88:89]
	v_pk_add_f32 v[110:111], v[110:111], v[86:87]
	v_pk_add_f32 v[108:109], v[108:109], v[84:85]
	s_and_b64 vcc, exec, s[38:39]
	v_pk_add_f32 v[114:115], v[106:107], v[82:83]
	v_cvt_pk_bf16_f32 v121, v116, v117
	global_store_dwordx4 v[122:123], v[118:121], off offset:256 sc1
	s_cbranch_vccnz .LBB0_575
	s_mov_b32 s100, 0xbfb8aa3b
	v_pk_mul_f32 v[108:109], v[108:109], s[100:101] op_sel_hi:[1,0]
	v_pk_mul_f32 v[110:111], v[110:111], s[100:101] op_sel_hi:[1,0]
	v_pk_mul_f32 v[112:113], v[112:113], s[100:101] op_sel_hi:[1,0]
	v_pk_mul_f32 v[114:115], v[114:115], s[100:101] op_sel_hi:[1,0]
	v_exp_f32_e32 v108, v108
	v_exp_f32_e32 v109, v109
	v_exp_f32_e32 v110, v110
	v_exp_f32_e32 v111, v111
	v_exp_f32_e32 v112, v112
	v_exp_f32_e32 v113, v113
	v_exp_f32_e32 v114, v114
	v_exp_f32_e32 v115, v115
	v_pk_add_f32 v[108:109], v[108:109], 1.0 op_sel_hi:[1,0]
	v_pk_add_f32 v[110:111], v[110:111], 1.0 op_sel_hi:[1,0]
	v_pk_add_f32 v[112:113], v[112:113], 1.0 op_sel_hi:[1,0]
	v_pk_add_f32 v[114:115], v[114:115], 1.0 op_sel_hi:[1,0]
	v_rcp_f32_e32 v108, v108
	v_rcp_f32_e32 v109, v109
	v_rcp_f32_e32 v110, v110
	v_rcp_f32_e32 v111, v111
	v_rcp_f32_e32 v112, v112
	v_rcp_f32_e32 v113, v113
	v_rcp_f32_e32 v114, v114
	v_rcp_f32_e32 v115, v115
.LBB0_575:
	v_or_b32_e32 v106, 32, v166
	v_mad_i64_i32 v[106:107], s[14:15], s13, v106, 0
	v_lshl_add_u64 v[106:107], v[106:107], 1, v[138:139]
	v_pk_add_f32 v[104:105], v[104:105], v[76:77]
	v_pk_add_f32 v[102:103], v[102:103], v[74:75]
	v_pk_add_f32 v[100:101], v[100:101], v[68:69]
	s_and_b64 vcc, exec, s[38:39]
	v_pk_add_f32 v[98:99], v[98:99], v[66:67]
	v_cvt_pk_bf16_f32 v110, v110, v111
	v_cvt_pk_bf16_f32 v111, v112, v113
	v_cvt_pk_bf16_f32 v112, v114, v115
	v_cvt_pk_bf16_f32 v113, v108, v109
	global_store_dwordx4 v[106:107], v[110:113], off sc1
	s_cbranch_vccnz .LBB0_577
	s_mov_b32 s100, 0xbfb8aa3b
	v_pk_mul_f32 v[98:99], v[98:99], s[100:101] op_sel_hi:[1,0]
	v_pk_mul_f32 v[100:101], v[100:101], s[100:101] op_sel_hi:[1,0]
	v_pk_mul_f32 v[102:103], v[102:103], s[100:101] op_sel_hi:[1,0]
	v_pk_mul_f32 v[104:105], v[104:105], s[100:101] op_sel_hi:[1,0]
	v_exp_f32_e32 v98, v98
	v_exp_f32_e32 v99, v99
	v_exp_f32_e32 v100, v100
	v_exp_f32_e32 v101, v101
	v_exp_f32_e32 v102, v102
	v_exp_f32_e32 v103, v103
	v_exp_f32_e32 v104, v104
	v_exp_f32_e32 v105, v105
	v_pk_add_f32 v[98:99], v[98:99], 1.0 op_sel_hi:[1,0]
	v_pk_add_f32 v[100:101], v[100:101], 1.0 op_sel_hi:[1,0]
	v_pk_add_f32 v[102:103], v[102:103], 1.0 op_sel_hi:[1,0]
	v_pk_add_f32 v[104:105], v[104:105], 1.0 op_sel_hi:[1,0]
	v_rcp_f32_e32 v98, v98
	v_rcp_f32_e32 v99, v99
	v_rcp_f32_e32 v100, v100
	v_rcp_f32_e32 v101, v101
	v_rcp_f32_e32 v102, v102
	v_rcp_f32_e32 v103, v103
	v_rcp_f32_e32 v104, v104
	v_rcp_f32_e32 v105, v105
.LBB0_577:
	v_cvt_pk_bf16_f32 v102, v102, v103
	v_cvt_pk_bf16_f32 v103, v104, v105
	v_cvt_pk_bf16_f32 v104, v98, v99
	v_pk_add_f32 v[96:97], v[96:97], v[88:89]
	v_pk_add_f32 v[94:95], v[94:95], v[86:87]
	v_pk_add_f32 v[92:93], v[92:93], v[84:85]
	s_and_b64 vcc, exec, s[38:39]
	v_pk_add_f32 v[98:99], v[90:91], v[82:83]
	v_cvt_pk_bf16_f32 v105, v100, v101
	global_store_dwordx4 v[106:107], v[102:105], off offset:256 sc1
	s_cbranch_vccnz .LBB0_579
	s_mov_b32 s100, 0xbfb8aa3b
	v_pk_mul_f32 v[92:93], v[92:93], s[100:101] op_sel_hi:[1,0]
	v_pk_mul_f32 v[94:95], v[94:95], s[100:101] op_sel_hi:[1,0]
	v_pk_mul_f32 v[96:97], v[96:97], s[100:101] op_sel_hi:[1,0]
	v_pk_mul_f32 v[98:99], v[98:99], s[100:101] op_sel_hi:[1,0]
	v_exp_f32_e32 v92, v92
	v_exp_f32_e32 v93, v93
	v_exp_f32_e32 v94, v94
	v_exp_f32_e32 v95, v95
	v_exp_f32_e32 v96, v96
	v_exp_f32_e32 v97, v97
	v_exp_f32_e32 v98, v98
	v_exp_f32_e32 v99, v99
	v_pk_add_f32 v[92:93], v[92:93], 1.0 op_sel_hi:[1,0]
	v_pk_add_f32 v[94:95], v[94:95], 1.0 op_sel_hi:[1,0]
	v_pk_add_f32 v[96:97], v[96:97], 1.0 op_sel_hi:[1,0]
	v_pk_add_f32 v[98:99], v[98:99], 1.0 op_sel_hi:[1,0]
	v_rcp_f32_e32 v92, v92
	v_rcp_f32_e32 v93, v93
	v_rcp_f32_e32 v94, v94
	v_rcp_f32_e32 v95, v95
	v_rcp_f32_e32 v96, v96
	v_rcp_f32_e32 v97, v97
	v_rcp_f32_e32 v98, v98
	v_rcp_f32_e32 v99, v99
.LBB0_579:
	v_or_b32_e32 v90, 48, v166
	v_mad_i64_i32 v[90:91], s[14:15], s13, v90, 0
	v_lshl_add_u64 v[90:91], v[90:91], 1, v[138:139]
	v_pk_add_f32 v[80:81], v[80:81], v[76:77]
	v_pk_add_f32 v[78:79], v[78:79], v[74:75]
	v_pk_add_f32 v[72:73], v[72:73], v[68:69]
	s_and_b64 vcc, exec, s[38:39]
	v_pk_add_f32 v[70:71], v[70:71], v[66:67]
	v_cvt_pk_bf16_f32 v94, v94, v95
	v_cvt_pk_bf16_f32 v95, v96, v97
	v_cvt_pk_bf16_f32 v96, v98, v99
	v_cvt_pk_bf16_f32 v97, v92, v93
	global_store_dwordx4 v[90:91], v[94:97], off sc1
	s_cbranch_vccnz .LBB0_581
	s_mov_b32 s100, 0xbfb8aa3b
	v_pk_mul_f32 v[70:71], v[70:71], s[100:101] op_sel_hi:[1,0]
	v_pk_mul_f32 v[72:73], v[72:73], s[100:101] op_sel_hi:[1,0]
	v_pk_mul_f32 v[78:79], v[78:79], s[100:101] op_sel_hi:[1,0]
	v_pk_mul_f32 v[80:81], v[80:81], s[100:101] op_sel_hi:[1,0]
	v_exp_f32_e32 v70, v70
	v_exp_f32_e32 v71, v71
	v_exp_f32_e32 v72, v72
	v_exp_f32_e32 v73, v73
	v_exp_f32_e32 v78, v78
	v_exp_f32_e32 v79, v79
	v_exp_f32_e32 v80, v80
	v_exp_f32_e32 v81, v81
	v_pk_add_f32 v[70:71], v[70:71], 1.0 op_sel_hi:[1,0]
	v_pk_add_f32 v[72:73], v[72:73], 1.0 op_sel_hi:[1,0]
	v_pk_add_f32 v[78:79], v[78:79], 1.0 op_sel_hi:[1,0]
	v_pk_add_f32 v[80:81], v[80:81], 1.0 op_sel_hi:[1,0]
	v_rcp_f32_e32 v70, v70
	v_rcp_f32_e32 v71, v71
	v_rcp_f32_e32 v72, v72
	v_rcp_f32_e32 v73, v73
	v_rcp_f32_e32 v78, v78
	v_rcp_f32_e32 v79, v79
	v_rcp_f32_e32 v80, v80
	v_rcp_f32_e32 v81, v81
; __device__ __forceinline__ unsigned cvt_pk_bf16(float lo, float hi) { unsigned r; asm volatile("v_cvt_pk_bf16_f32 %0, %1, %2" : "=v"(r) : "v"(lo), "v"(hi)); return r; }
;     __device__ __forceinline__ void operator()(const f32x4 (&acc)[2][2][4][2], const Unit& u, int wr, int wc, int fr, int fq) const {
;     ...
;         for (int ai = 0; ai < 2; ++ai)
; #pragma unroll
;             for (int m = 0; m < 4; ++m) { bf16_t* rowp = base + (size_t)(row0 + ai * HALF + m * 16) * ld + col0;
; #pragma unroll
;                 for (int bj = 0; bj < 2; ++bj) { f32x4 v0 = acc[ai][bj][m][0] + bv[bj][0], v1 = acc[ai][bj][m][1] + bv[bj][1];
;                     if (sig) {
; #pragma unroll
;                         for (int j = 0; j < 4; ++j) { v0[j] = __builtin_amdgcn_rcpf(1.0f + __expf(-v0[j])); v1[j] = __builtin_amdgcn_rcpf(1.0f + __expf(-v1[j])); } }
;                     u32x4 w; w.x = cvt_pk_bf16(v0[0], v0[1]); w.y = cvt_pk_bf16(v0[2], v0[3]); w.z = cvt_pk_bf16(v1[0], v1[1]); w.w = cvt_pk_bf16(v1[2], v1[3]);
;                     *(u32x4*)(rowp + bj * HALF) = w; } }
.LBB0_581:
	v_cvt_pk_bf16_f32 v78, v78, v79
	v_cvt_pk_bf16_f32 v79, v80, v81
	v_cvt_pk_bf16_f32 v80, v70, v71
	v_pk_add_f32 v[64:65], v[64:65], v[88:89]
	v_pk_add_f32 v[62:63], v[62:63], v[86:87]
	v_pk_add_f32 v[60:61], v[60:61], v[84:85]
	s_and_b64 vcc, exec, s[38:39]
	v_pk_add_f32 v[70:71], v[58:59], v[82:83]
	v_cvt_pk_bf16_f32 v81, v72, v73
	global_store_dwordx4 v[90:91], v[78:81], off offset:256 sc1
	s_cbranch_vccnz .LBB0_583
	s_mov_b32 s100, 0xbfb8aa3b
	v_pk_mul_f32 v[60:61], v[60:61], s[100:101] op_sel_hi:[1,0]
	v_pk_mul_f32 v[62:63], v[62:63], s[100:101] op_sel_hi:[1,0]
	v_pk_mul_f32 v[64:65], v[64:65], s[100:101] op_sel_hi:[1,0]
	v_pk_mul_f32 v[70:71], v[70:71], s[100:101] op_sel_hi:[1,0]
	v_exp_f32_e32 v60, v60
	v_exp_f32_e32 v61, v61
	v_exp_f32_e32 v62, v62
	v_exp_f32_e32 v63, v63
	v_exp_f32_e32 v64, v64
	v_exp_f32_e32 v65, v65
	v_exp_f32_e32 v70, v70
	v_exp_f32_e32 v71, v71
	v_pk_add_f32 v[60:61], v[60:61], 1.0 op_sel_hi:[1,0]
	v_pk_add_f32 v[62:63], v[62:63], 1.0 op_sel_hi:[1,0]
	v_pk_add_f32 v[64:65], v[64:65], 1.0 op_sel_hi:[1,0]
	v_pk_add_f32 v[70:71], v[70:71], 1.0 op_sel_hi:[1,0]
	v_rcp_f32_e32 v60, v60
	v_rcp_f32_e32 v61, v61
	v_rcp_f32_e32 v62, v62
	v_rcp_f32_e32 v63, v63
	v_rcp_f32_e32 v64, v64
	v_rcp_f32_e32 v65, v65
	v_rcp_f32_e32 v70, v70
	v_rcp_f32_e32 v71, v71
.LBB0_583:
	v_add_u32_e32 v58, 0x80, v166
	v_mad_i64_i32 v[58:59], s[14:15], s13, v58, 0
	v_lshl_add_u64 v[58:59], v[58:59], 1, v[138:139]
	v_pk_add_f32 v[56:57], v[56:57], v[76:77]
	v_pk_add_f32 v[54:55], v[54:55], v[74:75]
	v_pk_add_f32 v[52:53], v[52:53], v[68:69]
	s_and_b64 vcc, exec, s[38:39]
	v_pk_add_f32 v[50:51], v[50:51], v[66:67]
	v_cvt_pk_bf16_f32 v62, v62, v63
	v_cvt_pk_bf16_f32 v63, v64, v65
	v_cvt_pk_bf16_f32 v64, v70, v71
	v_cvt_pk_bf16_f32 v65, v60, v61
	global_store_dwordx4 v[58:59], v[62:65], off sc1
	s_cbranch_vccnz .LBB0_585
	s_mov_b32 s100, 0xbfb8aa3b
	v_pk_mul_f32 v[50:51], v[50:51], s[100:101] op_sel_hi:[1,0]
	v_pk_mul_f32 v[52:53], v[52:53], s[100:101] op_sel_hi:[1,0]
	v_pk_mul_f32 v[54:55], v[54:55], s[100:101] op_sel_hi:[1,0]
	v_pk_mul_f32 v[56:57], v[56:57], s[100:101] op_sel_hi:[1,0]
	v_exp_f32_e32 v50, v50
	v_exp_f32_e32 v51, v51
	v_exp_f32_e32 v52, v52
	v_exp_f32_e32 v53, v53
	v_exp_f32_e32 v54, v54
	v_exp_f32_e32 v55, v55
	v_exp_f32_e32 v56, v56
	v_exp_f32_e32 v57, v57
	v_pk_add_f32 v[50:51], v[50:51], 1.0 op_sel_hi:[1,0]
	v_pk_add_f32 v[52:53], v[52:53], 1.0 op_sel_hi:[1,0]
	v_pk_add_f32 v[54:55], v[54:55], 1.0 op_sel_hi:[1,0]
	v_pk_add_f32 v[56:57], v[56:57], 1.0 op_sel_hi:[1,0]
	v_rcp_f32_e32 v50, v50
	v_rcp_f32_e32 v51, v51
	v_rcp_f32_e32 v52, v52
	v_rcp_f32_e32 v53, v53
	v_rcp_f32_e32 v54, v54
	v_rcp_f32_e32 v55, v55
	v_rcp_f32_e32 v56, v56
	v_rcp_f32_e32 v57, v57
.LBB0_585:
	v_cvt_pk_bf16_f32 v54, v54, v55
	v_cvt_pk_bf16_f32 v55, v56, v57
	v_cvt_pk_bf16_f32 v56, v50, v51
	v_pk_add_f32 v[48:49], v[48:49], v[88:89]
	v_pk_add_f32 v[46:47], v[46:47], v[86:87]
	v_pk_add_f32 v[44:45], v[44:45], v[84:85]
	s_and_b64 vcc, exec, s[38:39]
	v_pk_add_f32 v[50:51], v[42:43], v[82:83]
	v_cvt_pk_bf16_f32 v57, v52, v53
	global_store_dwordx4 v[58:59], v[54:57], off offset:256 sc1
	s_cbranch_vccnz .LBB0_587
	s_mov_b32 s100, 0xbfb8aa3b
	v_pk_mul_f32 v[44:45], v[44:45], s[100:101] op_sel_hi:[1,0]
	v_pk_mul_f32 v[46:47], v[46:47], s[100:101] op_sel_hi:[1,0]
	v_pk_mul_f32 v[48:49], v[48:49], s[100:101] op_sel_hi:[1,0]
	v_pk_mul_f32 v[50:51], v[50:51], s[100:101] op_sel_hi:[1,0]
	v_exp_f32_e32 v44, v44
	v_exp_f32_e32 v45, v45
	v_exp_f32_e32 v46, v46
	v_exp_f32_e32 v47, v47
	v_exp_f32_e32 v48, v48
	v_exp_f32_e32 v49, v49
	v_exp_f32_e32 v50, v50
	v_exp_f32_e32 v51, v51
	v_pk_add_f32 v[44:45], v[44:45], 1.0 op_sel_hi:[1,0]
	v_pk_add_f32 v[46:47], v[46:47], 1.0 op_sel_hi:[1,0]
	v_pk_add_f32 v[48:49], v[48:49], 1.0 op_sel_hi:[1,0]
	v_pk_add_f32 v[50:51], v[50:51], 1.0 op_sel_hi:[1,0]
	v_rcp_f32_e32 v44, v44
	v_rcp_f32_e32 v45, v45
	v_rcp_f32_e32 v46, v46
	v_rcp_f32_e32 v47, v47
	v_rcp_f32_e32 v48, v48
	v_rcp_f32_e32 v49, v49
	v_rcp_f32_e32 v50, v50
	v_rcp_f32_e32 v51, v51
.LBB0_587:
	v_add_u32_e32 v42, 0x90, v166
	v_mad_i64_i32 v[42:43], s[14:15], s13, v42, 0
	v_lshl_add_u64 v[42:43], v[42:43], 1, v[138:139]
	v_pk_add_f32 v[40:41], v[40:41], v[76:77]
	v_pk_add_f32 v[38:39], v[38:39], v[74:75]
	v_pk_add_f32 v[36:37], v[36:37], v[68:69]
	s_and_b64 vcc, exec, s[38:39]
	v_pk_add_f32 v[34:35], v[34:35], v[66:67]
	v_cvt_pk_bf16_f32 v46, v46, v47
	v_cvt_pk_bf16_f32 v47, v48, v49
	v_cvt_pk_bf16_f32 v48, v50, v51
	v_cvt_pk_bf16_f32 v49, v44, v45
	global_store_dwordx4 v[42:43], v[46:49], off sc1
	s_cbranch_vccnz .LBB0_589
	s_mov_b32 s100, 0xbfb8aa3b
	v_pk_mul_f32 v[34:35], v[34:35], s[100:101] op_sel_hi:[1,0]
	v_pk_mul_f32 v[36:37], v[36:37], s[100:101] op_sel_hi:[1,0]
	v_pk_mul_f32 v[38:39], v[38:39], s[100:101] op_sel_hi:[1,0]
	v_pk_mul_f32 v[40:41], v[40:41], s[100:101] op_sel_hi:[1,0]
	v_exp_f32_e32 v34, v34
	v_exp_f32_e32 v35, v35
	v_exp_f32_e32 v36, v36
	v_exp_f32_e32 v37, v37
	v_exp_f32_e32 v38, v38
	v_exp_f32_e32 v39, v39
	v_exp_f32_e32 v40, v40
	v_exp_f32_e32 v41, v41
	v_pk_add_f32 v[34:35], v[34:35], 1.0 op_sel_hi:[1,0]
	v_pk_add_f32 v[36:37], v[36:37], 1.0 op_sel_hi:[1,0]
	v_pk_add_f32 v[38:39], v[38:39], 1.0 op_sel_hi:[1,0]
	v_pk_add_f32 v[40:41], v[40:41], 1.0 op_sel_hi:[1,0]
	v_rcp_f32_e32 v34, v34
	v_rcp_f32_e32 v35, v35
	v_rcp_f32_e32 v36, v36
	v_rcp_f32_e32 v37, v37
	v_rcp_f32_e32 v38, v38
	v_rcp_f32_e32 v39, v39
	v_rcp_f32_e32 v40, v40
	v_rcp_f32_e32 v41, v41
; __device__ __forceinline__ unsigned cvt_pk_bf16(float lo, float hi) { unsigned r; asm volatile("v_cvt_pk_bf16_f32 %0, %1, %2" : "=v"(r) : "v"(lo), "v"(hi)); return r; }
;     __device__ __forceinline__ void operator()(const f32x4 (&acc)[2][2][4][2], const Unit& u, int wr, int wc, int fr, int fq) const {
;     ...
;         for (int ai = 0; ai < 2; ++ai)
; #pragma unroll
;             for (int m = 0; m < 4; ++m) { bf16_t* rowp = base + (size_t)(row0 + ai * HALF + m * 16) * ld + col0;
; #pragma unroll
;                 for (int bj = 0; bj < 2; ++bj) { f32x4 v0 = acc[ai][bj][m][0] + bv[bj][0], v1 = acc[ai][bj][m][1] + bv[bj][1];
;                     if (sig) {
; #pragma unroll
;                         for (int j = 0; j < 4; ++j) { v0[j] = __builtin_amdgcn_rcpf(1.0f + __expf(-v0[j])); v1[j] = __builtin_amdgcn_rcpf(1.0f + __expf(-v1[j])); } }
;                     u32x4 w; w.x = cvt_pk_bf16(v0[0], v0[1]); w.y = cvt_pk_bf16(v0[2], v0[3]); w.z = cvt_pk_bf16(v1[0], v1[1]); w.w = cvt_pk_bf16(v1[2], v1[3]);
;                     *(u32x4*)(rowp + bj * HALF) = w; } }
.LBB0_589:
	v_cvt_pk_bf16_f32 v38, v38, v39
	v_cvt_pk_bf16_f32 v39, v40, v41
	v_cvt_pk_bf16_f32 v40, v34, v35
	v_pk_add_f32 v[32:33], v[32:33], v[88:89]
	v_pk_add_f32 v[30:31], v[30:31], v[86:87]
	v_pk_add_f32 v[28:29], v[28:29], v[84:85]
	s_and_b64 vcc, exec, s[38:39]
	v_pk_add_f32 v[34:35], v[26:27], v[82:83]
	v_cvt_pk_bf16_f32 v41, v36, v37
	global_store_dwordx4 v[42:43], v[38:41], off offset:256 sc1
	s_cbranch_vccnz .LBB0_591
	s_mov_b32 s100, 0xbfb8aa3b
	v_pk_mul_f32 v[28:29], v[28:29], s[100:101] op_sel_hi:[1,0]
	v_pk_mul_f32 v[30:31], v[30:31], s[100:101] op_sel_hi:[1,0]
	v_pk_mul_f32 v[32:33], v[32:33], s[100:101] op_sel_hi:[1,0]
	v_pk_mul_f32 v[34:35], v[34:35], s[100:101] op_sel_hi:[1,0]
	v_exp_f32_e32 v28, v28
	v_exp_f32_e32 v29, v29
	v_exp_f32_e32 v30, v30
	v_exp_f32_e32 v31, v31
	v_exp_f32_e32 v32, v32
	v_exp_f32_e32 v33, v33
	v_exp_f32_e32 v34, v34
	v_exp_f32_e32 v35, v35
	v_pk_add_f32 v[28:29], v[28:29], 1.0 op_sel_hi:[1,0]
	v_pk_add_f32 v[30:31], v[30:31], 1.0 op_sel_hi:[1,0]
	v_pk_add_f32 v[32:33], v[32:33], 1.0 op_sel_hi:[1,0]
	v_pk_add_f32 v[34:35], v[34:35], 1.0 op_sel_hi:[1,0]
	v_rcp_f32_e32 v28, v28
	v_rcp_f32_e32 v29, v29
	v_rcp_f32_e32 v30, v30
	v_rcp_f32_e32 v31, v31
	v_rcp_f32_e32 v32, v32
	v_rcp_f32_e32 v33, v33
	v_rcp_f32_e32 v34, v34
	v_rcp_f32_e32 v35, v35
.LBB0_591:
	v_add_u32_e32 v26, 0xa0, v166
	v_mad_i64_i32 v[26:27], s[14:15], s13, v26, 0
	v_lshl_add_u64 v[26:27], v[26:27], 1, v[138:139]
	v_pk_add_f32 v[24:25], v[24:25], v[76:77]
	v_pk_add_f32 v[22:23], v[22:23], v[74:75]
	v_pk_add_f32 v[20:21], v[20:21], v[68:69]
	s_and_b64 vcc, exec, s[38:39]
	v_pk_add_f32 v[18:19], v[18:19], v[66:67]
	v_cvt_pk_bf16_f32 v30, v30, v31
	v_cvt_pk_bf16_f32 v31, v32, v33
	v_cvt_pk_bf16_f32 v32, v34, v35
	v_cvt_pk_bf16_f32 v33, v28, v29
	global_store_dwordx4 v[26:27], v[30:33], off sc1
	s_cbranch_vccnz .LBB0_593
	s_mov_b32 s100, 0xbfb8aa3b
	v_pk_mul_f32 v[18:19], v[18:19], s[100:101] op_sel_hi:[1,0]
	v_pk_mul_f32 v[20:21], v[20:21], s[100:101] op_sel_hi:[1,0]
	v_pk_mul_f32 v[22:23], v[22:23], s[100:101] op_sel_hi:[1,0]
	v_pk_mul_f32 v[24:25], v[24:25], s[100:101] op_sel_hi:[1,0]
	v_exp_f32_e32 v18, v18
	v_exp_f32_e32 v19, v19
	v_exp_f32_e32 v20, v20
	v_exp_f32_e32 v21, v21
	v_exp_f32_e32 v22, v22
	v_exp_f32_e32 v23, v23
	v_exp_f32_e32 v24, v24
	v_exp_f32_e32 v25, v25
	v_pk_add_f32 v[18:19], v[18:19], 1.0 op_sel_hi:[1,0]
	v_pk_add_f32 v[20:21], v[20:21], 1.0 op_sel_hi:[1,0]
	v_pk_add_f32 v[22:23], v[22:23], 1.0 op_sel_hi:[1,0]
	v_pk_add_f32 v[24:25], v[24:25], 1.0 op_sel_hi:[1,0]
	v_rcp_f32_e32 v18, v18
	v_rcp_f32_e32 v19, v19
	v_rcp_f32_e32 v20, v20
	v_rcp_f32_e32 v21, v21
	v_rcp_f32_e32 v22, v22
	v_rcp_f32_e32 v23, v23
	v_rcp_f32_e32 v24, v24
	v_rcp_f32_e32 v25, v25
.LBB0_593:
	v_cvt_pk_bf16_f32 v22, v22, v23
	v_cvt_pk_bf16_f32 v23, v24, v25
	v_cvt_pk_bf16_f32 v24, v18, v19
	v_pk_add_f32 v[16:17], v[16:17], v[88:89]
	v_pk_add_f32 v[14:15], v[14:15], v[86:87]
	v_pk_add_f32 v[12:13], v[12:13], v[84:85]
	s_and_b64 vcc, exec, s[38:39]
	v_pk_add_f32 v[18:19], v[10:11], v[82:83]
	v_cvt_pk_bf16_f32 v25, v20, v21
	global_store_dwordx4 v[26:27], v[22:25], off offset:256 sc1
	s_cbranch_vccnz .LBB0_595
	s_mov_b32 s100, 0xbfb8aa3b
	v_pk_mul_f32 v[12:13], v[12:13], s[100:101] op_sel_hi:[1,0]
	v_pk_mul_f32 v[14:15], v[14:15], s[100:101] op_sel_hi:[1,0]
	v_pk_mul_f32 v[16:17], v[16:17], s[100:101] op_sel_hi:[1,0]
	v_pk_mul_f32 v[18:19], v[18:19], s[100:101] op_sel_hi:[1,0]
	v_exp_f32_e32 v12, v12
	v_exp_f32_e32 v13, v13
	v_exp_f32_e32 v14, v14
	v_exp_f32_e32 v15, v15
	v_exp_f32_e32 v16, v16
	v_exp_f32_e32 v17, v17
	v_exp_f32_e32 v18, v18
	v_exp_f32_e32 v19, v19
	v_pk_add_f32 v[12:13], v[12:13], 1.0 op_sel_hi:[1,0]
	v_pk_add_f32 v[14:15], v[14:15], 1.0 op_sel_hi:[1,0]
	v_pk_add_f32 v[16:17], v[16:17], 1.0 op_sel_hi:[1,0]
	v_pk_add_f32 v[18:19], v[18:19], 1.0 op_sel_hi:[1,0]
	v_rcp_f32_e32 v12, v12
	v_rcp_f32_e32 v13, v13
	v_rcp_f32_e32 v14, v14
	v_rcp_f32_e32 v15, v15
	v_rcp_f32_e32 v16, v16
	v_rcp_f32_e32 v17, v17
	v_rcp_f32_e32 v18, v18
	v_rcp_f32_e32 v19, v19
.LBB0_595:
	v_add_u32_e32 v10, 0xb0, v166
	v_mad_i64_i32 v[10:11], s[14:15], s13, v10, 0
	v_lshl_add_u64 v[10:11], v[10:11], 1, v[138:139]
	v_pk_add_f32 v[8:9], v[8:9], v[76:77]
	v_pk_add_f32 v[6:7], v[6:7], v[74:75]
	v_pk_add_f32 v[4:5], v[4:5], v[68:69]
	s_and_b64 vcc, exec, s[38:39]
	v_pk_add_f32 v[2:3], v[2:3], v[66:67]
	v_cvt_pk_bf16_f32 v14, v14, v15
	v_cvt_pk_bf16_f32 v15, v16, v17
	v_cvt_pk_bf16_f32 v16, v18, v19
	v_cvt_pk_bf16_f32 v17, v12, v13
	global_store_dwordx4 v[10:11], v[14:17], off sc1
	s_cbranch_vccnz .LBB0_597
	s_mov_b32 s100, 0xbfb8aa3b
	v_pk_mul_f32 v[2:3], v[2:3], s[100:101] op_sel_hi:[1,0]
	v_pk_mul_f32 v[4:5], v[4:5], s[100:101] op_sel_hi:[1,0]
	v_pk_mul_f32 v[6:7], v[6:7], s[100:101] op_sel_hi:[1,0]
	v_pk_mul_f32 v[8:9], v[8:9], s[100:101] op_sel_hi:[1,0]
	v_exp_f32_e32 v2, v2
	v_exp_f32_e32 v3, v3
	v_exp_f32_e32 v4, v4
	v_exp_f32_e32 v5, v5
	v_exp_f32_e32 v6, v6
	v_exp_f32_e32 v7, v7
	v_exp_f32_e32 v8, v8
	v_exp_f32_e32 v9, v9
	v_pk_add_f32 v[2:3], v[2:3], 1.0 op_sel_hi:[1,0]
	v_pk_add_f32 v[4:5], v[4:5], 1.0 op_sel_hi:[1,0]
	v_pk_add_f32 v[6:7], v[6:7], 1.0 op_sel_hi:[1,0]
	v_pk_add_f32 v[8:9], v[8:9], 1.0 op_sel_hi:[1,0]
	v_rcp_f32_e32 v2, v2
	v_rcp_f32_e32 v3, v3
	v_rcp_f32_e32 v4, v4
	v_rcp_f32_e32 v5, v5
	v_rcp_f32_e32 v6, v6
	v_rcp_f32_e32 v7, v7
	v_rcp_f32_e32 v8, v8
	v_rcp_f32_e32 v9, v9
